# lever 2 prologue de-serialisation in glapre: next unit's LR rows requested at the start of the current unit's gate loop (held in free VGPRs, written to LDS at the next unit start) instead of load+vmcn
# baseline (speedup 1.0000x reference)
.Lgl_lrpf_use:
	ds_write_b128 v72, v[206:209]
.LBB0_611:
	s_or_b64 exec, exec, s[62:63]
	s_lshl_b32 s0, s36, 8
	s_and_b32 s0, s0, 0x700
	s_lshl_b32 s0, s0, 1
	s_add_u32 s62, s56, s0
	s_addc_u32 s63, s57, 0
	v_mov_b32_e32 v69, v1
	v_lshl_add_u64 v[42:43], s[62:63], 0, v[68:69]
	v_add_u32_e32 v0, s38, v73
	v_mad_i64_i32 v[18:19], s[64:65], v0, s80, v[42:43]
	v_add_co_u32_e32 v22, vcc, s81, v18
	v_add_u32_e32 v0, s38, v74
	s_nop 0
	v_addc_co_u32_e32 v23, vcc, 0, v19, vcc
	v_mad_i64_i32 v[26:27], s[64:65], v0, s80, v[42:43]
	v_add_co_u32_e32 v30, vcc, s81, v26
	v_add_u32_e32 v0, s38, v75
	s_nop 0
	v_addc_co_u32_e32 v31, vcc, 0, v27, vcc
	v_mad_i64_i32 v[34:35], s[64:65], v0, s80, v[42:43]
	v_add_co_u32_e32 v38, vcc, s81, v34
	v_add_u32_e32 v0, s38, v76
	s_nop 0
	v_addc_co_u32_e32 v39, vcc, 0, v35, vcc
	v_mad_i64_i32 v[42:43], s[64:65], v0, s80, v[42:43]
	v_add_co_u32_e32 v46, vcc, s81, v42
	global_load_dwordx4 v[18:21], v[18:19], off
	s_nop 0
	global_load_dwordx4 v[22:25], v[22:23], off
	v_addc_co_u32_e32 v47, vcc, 0, v43, vcc
	global_load_dwordx4 v[26:29], v[26:27], off
	s_nop 0
	global_load_dwordx4 v[30:33], v[30:31], off
	s_nop 0
	global_load_dwordx4 v[34:37], v[34:35], off
	s_nop 0
	global_load_dwordx4 v[38:41], v[38:39], off
	s_nop 0
	global_load_dwordx4 v[42:45], v[42:43], off
	s_nop 0
	global_load_dwordx4 v[46:49], v[46:47], off
	s_waitcnt lgkmcnt(0)
	s_barrier
	s_add_i32 s98, s36, s68
	s_min_u32 s98, s98, 0x7ff
	s_lshl_b32 s98, s98, 3
	s_and_b32 s98, s98, 0xffffffc0
	s_mov_b32 s99, 0
	s_lshl_b64 s[100:101], s[98:99], 6
	s_and_saveexec_b64 s[98:99], s[2:3]
	v_lshl_add_u64 v[210:211], v[52:53], 0, s[100:101]
	global_load_dwordx4 v[206:209], v[210:211], off
	s_or_b64 exec, exec, s[98:99]
	ds_read_b128 v[120:123], v77
	ds_read_b128 v[124:127], v77 offset:16
	ds_read_b128 v[128:131], v77 offset:32
	ds_read_b128 v[132:135], v77 offset:48
	ds_read_b128 v[136:139], v77 offset:64
	ds_read_b128 v[140:143], v77 offset:80
	ds_read_b128 v[144:147], v77 offset:96
	ds_read_b128 v[148:151], v77 offset:112
	ds_read_b128 v[152:155], v77 offset:144
	ds_read_b128 v[156:159], v77 offset:128
	ds_read_b128 v[160:163], v77 offset:160
	ds_read_b128 v[164:167], v77 offset:176
	ds_read_b128 v[168:171], v77 offset:192
	ds_read_b128 v[172:175], v77 offset:208
	ds_read_b128 v[176:179], v77 offset:224
	ds_read_b128 v[180:183], v77 offset:240
	s_waitcnt vmcnt(25) lgkmcnt(15)
	v_mul_f32_e32 v0, v3, v121
	s_waitcnt vmcnt(23)
	v_mul_f32_e32 v69, v5, v123
	s_waitcnt vmcnt(10)
	v_fmac_f32_e32 v0, v2, v120
	v_fmac_f32_e32 v69, v4, v122
	v_add_f32_e32 v0, v0, v69
	s_waitcnt lgkmcnt(14)
	v_mul_f32_e32 v69, v7, v125
	v_mul_f32_e32 v80, v9, v127
	v_fmac_f32_e32 v69, v6, v124
	v_fmac_f32_e32 v80, v8, v126
	s_waitcnt vmcnt(9)
	v_add_f32_e32 v0, v79, v0
	v_add_f32_e32 v69, v69, v80
	v_add_f32_e32 v0, v0, v69
	s_waitcnt lgkmcnt(13)
	v_mul_f32_e32 v69, v11, v129
	v_mul_f32_e32 v80, v13, v131
	v_fmac_f32_e32 v69, v10, v128
	v_fmac_f32_e32 v80, v12, v130
	v_add_f32_e32 v69, v69, v80
	v_add_f32_e32 v0, v0, v69
	s_waitcnt lgkmcnt(12)
	v_mul_f32_e32 v69, v15, v133
	v_mul_f32_e32 v80, v17, v135
	v_fmac_f32_e32 v69, v14, v132
	v_fmac_f32_e32 v80, v16, v134
	v_add_f32_e32 v69, v69, v80
	ds_read_b128 v[120:123], v77 offset:256
	ds_read_b128 v[124:127], v77 offset:272
	v_add_f32_e32 v0, v0, v69
	v_mul_f32_e64 v69, |v0|, s82
	v_exp_f32_e32 v69, v69
	s_waitcnt lgkmcnt(13)
	v_mul_f32_e32 v81, v3, v137
	v_fmac_f32_e32 v81, v2, v136
	v_mul_f32_e32 v80, v5, v139
	v_fmac_f32_e32 v80, v4, v138
	v_add_f32_e32 v80, v81, v80
	s_waitcnt lgkmcnt(12)
	v_mul_f32_e32 v85, v7, v141
	v_add_f32_e32 v88, v79, v80
	v_fmac_f32_e32 v85, v6, v140
	v_mul_f32_e32 v84, v9, v143
	ds_read_b128 v[128:131], v77 offset:288
	v_fmac_f32_e32 v84, v8, v142
	v_add_f32_e32 v84, v85, v84
	v_add_f32_e32 v88, v88, v84
	ds_read_b128 v[132:135], v77 offset:304
	s_waitcnt lgkmcnt(13)
	v_mul_f32_e32 v81, v11, v145
	v_fmac_f32_e32 v81, v10, v144
	v_mul_f32_e32 v80, v13, v147
	v_fmac_f32_e32 v80, v12, v146
	v_add_f32_e32 v80, v81, v80
	s_waitcnt lgkmcnt(12)
	v_mul_f32_e32 v81, v15, v149
	v_mul_f32_e32 v82, v17, v151
	v_fmac_f32_e32 v81, v14, v148
	v_fmac_f32_e32 v82, v16, v150
	v_add_f32_e32 v80, v88, v80
	v_add_f32_e32 v81, v81, v82
	v_add_f32_e32 v84, v80, v81
	v_add_f32_e32 v69, 1.0, v69
	v_mul_f32_e64 v80, |v84|, s82
	v_log_f32_e32 v69, v69
	v_exp_f32_e32 v80, v80
	v_max_f32_e64 v0, -v0, 0
	ds_read_b128 v[136:139], v77 offset:320
	v_fmac_f32_e32 v0, 0x3f317218, v69
	v_add_f32_e32 v69, 1.0, v80
	ds_read_b128 v[140:143], v77 offset:336
	v_log_f32_e32 v69, v69
	v_fma_f32 v86, v0, s83, 0
	v_max_f32_e64 v0, -v84, 0
	s_waitcnt lgkmcnt(13)
	v_mul_f32_e32 v84, v7, v153
	v_fmac_f32_e32 v0, 0x3f317218, v69
	s_waitcnt lgkmcnt(12)
	v_mul_f32_e32 v69, v3, v157
	v_fmac_f32_e32 v69, v2, v156
	v_mul_f32_e32 v80, v5, v159
	v_fmac_f32_e32 v80, v4, v158
	v_add_f32_e32 v69, v69, v80
	ds_read_b128 v[144:147], v77 offset:352
	v_mul_f32_e32 v85, v9, v155
	v_fmac_f32_e32 v84, v6, v152
	v_fmac_f32_e32 v85, v8, v154
	ds_read_b128 v[148:151], v77 offset:368
	s_waitcnt lgkmcnt(13)
	v_mul_f32_e32 v81, v11, v161
	v_fmac_f32_e32 v81, v10, v160
	v_mul_f32_e32 v80, v13, v163
	v_add_f32_e32 v69, v79, v69
	v_add_f32_e32 v84, v84, v85
	v_fmac_f32_e32 v80, v12, v162
	v_add_f32_e32 v69, v69, v84
	v_add_f32_e32 v80, v81, v80
	v_add_f32_e32 v69, v69, v80
	s_waitcnt lgkmcnt(12)
	v_mul_f32_e32 v80, v15, v165
	v_mul_f32_e32 v81, v17, v167
	v_fmac_f32_e32 v80, v14, v164
	v_fmac_f32_e32 v81, v16, v166
	v_add_f32_e32 v80, v80, v81
	v_add_f32_e32 v69, v69, v80
	v_mul_f32_e64 v80, |v69|, s82
	v_exp_f32_e32 v84, v80
	ds_read_b128 v[152:155], v77 offset:384
	ds_read_b128 v[156:159], v77 offset:400
	v_max_f32_e64 v69, -v69, 0
	v_add_f32_e32 v84, 1.0, v84
	v_log_f32_e32 v84, v84
	s_waitcnt lgkmcnt(13)
	v_mul_f32_e32 v81, v3, v169
	v_fmac_f32_e32 v81, v2, v168
	v_mul_f32_e32 v80, v5, v171
	v_fmac_f32_e32 v80, v4, v170
	v_add_f32_e32 v80, v81, v80
	v_add_f32_e32 v85, v79, v80
	s_waitcnt lgkmcnt(12)
	v_mul_f32_e32 v87, v7, v173
	ds_read_b128 v[160:163], v77 offset:416
	v_fmac_f32_e32 v87, v6, v172
	v_mul_f32_e32 v88, v9, v175
	v_fmac_f32_e32 v88, v8, v174
	v_add_f32_e32 v87, v87, v88
	ds_read_b128 v[164:167], v77 offset:432
	s_waitcnt lgkmcnt(13)
	v_mul_f32_e32 v81, v11, v177
	v_fmac_f32_e32 v81, v10, v176
	v_mul_f32_e32 v80, v13, v179
	v_fmac_f32_e32 v80, v12, v178
	v_add_f32_e32 v80, v81, v80
	s_waitcnt lgkmcnt(12)
	v_mul_f32_e32 v81, v15, v181
	v_mul_f32_e32 v82, v17, v183
	v_add_f32_e32 v85, v85, v87
	v_fmac_f32_e32 v81, v14, v180
	v_fmac_f32_e32 v82, v16, v182
	v_add_f32_e32 v80, v85, v80
	v_add_f32_e32 v81, v81, v82
	v_add_f32_e32 v85, v80, v81
	v_mul_f32_e64 v80, |v85|, s82
	v_exp_f32_e32 v87, v80
	ds_read_b128 v[168:171], v77 offset:448
	ds_read_b128 v[172:175], v77 offset:464
	v_fmac_f32_e32 v69, 0x3f317218, v84
	v_add_f32_e32 v84, 1.0, v87
	v_log_f32_e32 v84, v84
	s_waitcnt lgkmcnt(13)
	v_mul_f32_e32 v81, v3, v121
	v_fmac_f32_e32 v81, v2, v120
	v_mul_f32_e32 v80, v5, v123
	v_fmac_f32_e32 v80, v4, v122
	v_add_f32_e32 v80, v81, v80
	s_waitcnt lgkmcnt(12)
	v_mul_f32_e32 v89, v7, v125
	v_add_f32_e32 v87, v79, v80
	v_fmac_f32_e32 v89, v6, v124
	v_mul_f32_e32 v88, v9, v127
	ds_read_b128 v[176:179], v77 offset:480
	v_fmac_f32_e32 v88, v8, v126
	v_add_f32_e32 v88, v89, v88
	v_add_f32_e32 v87, v87, v88
	ds_read_b128 v[180:183], v77 offset:496
	s_waitcnt lgkmcnt(13)
	v_mul_f32_e32 v81, v11, v129
	v_fmac_f32_e32 v81, v10, v128
	v_mul_f32_e32 v80, v13, v131
	v_fmac_f32_e32 v80, v12, v130
	v_add_f32_e32 v80, v81, v80
	s_waitcnt lgkmcnt(12)
	v_mul_f32_e32 v81, v15, v133
	v_mul_f32_e32 v82, v17, v135
	v_fmac_f32_e32 v81, v14, v132
	v_fmac_f32_e32 v82, v16, v134
	v_add_f32_e32 v80, v87, v80
	v_add_f32_e32 v81, v81, v82
	v_add_f32_e32 v87, v80, v81
	v_mul_f32_e64 v80, |v87|, s82
	v_exp_f32_e32 v88, v80
	ds_read_b128 v[120:123], v77 offset:512
	v_max_f32_e64 v85, -v85, 0
	v_fmac_f32_e32 v85, 0x3f317218, v84
	v_add_f32_e32 v84, 1.0, v88
	ds_read_b128 v[124:127], v77 offset:528
	s_waitcnt lgkmcnt(13)
	v_mul_f32_e32 v81, v3, v137
	v_fmac_f32_e32 v81, v2, v136
	v_mul_f32_e32 v80, v5, v139
	v_fmac_f32_e32 v80, v4, v138
	v_add_f32_e32 v80, v81, v80
	s_waitcnt lgkmcnt(12)
	v_mul_f32_e32 v89, v7, v141
	v_add_f32_e32 v92, v79, v80
	v_fmac_f32_e32 v89, v6, v140
	v_mul_f32_e32 v88, v9, v143
	ds_read_b128 v[128:131], v77 offset:544
	v_fmac_f32_e32 v88, v8, v142
	v_add_f32_e32 v88, v89, v88
	v_add_f32_e32 v92, v92, v88
	ds_read_b128 v[132:135], v77 offset:560
	s_waitcnt lgkmcnt(13)
	v_mul_f32_e32 v81, v11, v145
	v_fmac_f32_e32 v81, v10, v144
	v_mul_f32_e32 v80, v13, v147
	v_fmac_f32_e32 v80, v12, v146
	v_add_f32_e32 v80, v81, v80
	s_waitcnt lgkmcnt(12)
	v_mul_f32_e32 v81, v15, v149
	v_mul_f32_e32 v82, v17, v151
	v_fmac_f32_e32 v81, v14, v148
	v_fmac_f32_e32 v82, v16, v150
	v_add_f32_e32 v80, v92, v80
	v_add_f32_e32 v81, v81, v82
	v_add_f32_e32 v88, v80, v81
	v_mul_f32_e64 v80, |v88|, s82
	v_exp_f32_e32 v80, v80
	v_log_f32_e32 v84, v84
	v_fmamk_f32 v0, v0, 0xbd800000, v86
	v_fmamk_f32 v69, v69, 0xbd800000, v0
	v_add_f32_e32 v80, 1.0, v80
	v_max_f32_e64 v87, -v87, 0
	v_log_f32_e32 v89, v80
	v_fmamk_f32 v81, v85, 0xbd800000, v69
	v_fmac_f32_e32 v87, 0x3f317218, v84
	ds_read_b128 v[136:139], v77 offset:576
	v_fmamk_f32 v80, v87, 0xbd800000, v81
	v_max_f32_e64 v87, -v88, 0
	v_fmac_f32_e32 v87, 0x3f317218, v89
	ds_read_b128 v[140:143], v77 offset:592
	s_waitcnt lgkmcnt(13)
	v_mul_f32_e32 v83, v3, v153
	v_fmac_f32_e32 v83, v2, v152
	v_mul_f32_e32 v82, v5, v155
	v_fmac_f32_e32 v82, v4, v154
	v_add_f32_e32 v82, v83, v82
	s_waitcnt lgkmcnt(12)
	v_mul_f32_e32 v89, v7, v157
	v_add_f32_e32 v92, v79, v82
	v_fmac_f32_e32 v89, v6, v156
	v_mul_f32_e32 v88, v9, v159
	ds_read_b128 v[144:147], v77 offset:608
	v_fmac_f32_e32 v88, v8, v158
	v_add_f32_e32 v88, v89, v88
	v_add_f32_e32 v92, v92, v88
	ds_read_b128 v[148:151], v77 offset:624
	s_waitcnt lgkmcnt(13)
	v_mul_f32_e32 v83, v11, v161
	v_fmac_f32_e32 v83, v10, v160
	v_mul_f32_e32 v82, v13, v163
	v_fmac_f32_e32 v82, v12, v162
	v_add_f32_e32 v82, v83, v82
	s_waitcnt lgkmcnt(12)
	v_mul_f32_e32 v83, v15, v165
	v_mul_f32_e32 v84, v17, v167
	v_fmac_f32_e32 v83, v14, v164
	v_fmac_f32_e32 v84, v16, v166
	ds_read_b128 v[152:155], v77 offset:640
	v_add_f32_e32 v82, v92, v82
	v_add_f32_e32 v83, v83, v84
	ds_read_b128 v[156:159], v77 offset:656
	v_add_f32_e32 v83, v82, v83
	v_mul_f32_e64 v82, |v83|, s82
	v_exp_f32_e32 v84, v82
	v_fmamk_f32 v82, v87, 0xbd800000, v80
	s_waitcnt lgkmcnt(13)
	v_mul_f32_e32 v85, v3, v169
	v_mul_f32_e32 v87, v5, v171
	v_fmac_f32_e32 v85, v2, v168
	v_fmac_f32_e32 v87, v4, v170
	ds_read_b128 v[160:163], v77 offset:672
	v_add_f32_e32 v85, v85, v87
	s_waitcnt lgkmcnt(13)
	v_mul_f32_e32 v87, v7, v173
	v_fmac_f32_e32 v87, v6, v172
	v_mul_f32_e32 v92, v9, v175
	v_fmac_f32_e32 v92, v8, v174
	v_add_f32_e32 v85, v79, v85
	v_add_f32_e32 v87, v87, v92
	ds_read_b128 v[164:167], v77 offset:688
	v_add_f32_e32 v85, v85, v87
	s_waitcnt lgkmcnt(13)
	v_mul_f32_e32 v87, v11, v177
	v_fmac_f32_e32 v87, v10, v176
	v_mul_f32_e32 v88, v13, v179
	v_fmac_f32_e32 v88, v12, v178
	v_add_f32_e32 v87, v87, v88
	v_add_f32_e32 v85, v85, v87
	s_waitcnt lgkmcnt(12)
	v_mul_f32_e32 v87, v15, v181
	v_mul_f32_e32 v88, v17, v183
	v_fmac_f32_e32 v87, v14, v180
	v_fmac_f32_e32 v88, v16, v182
	v_add_f32_e32 v87, v87, v88
	v_add_f32_e32 v85, v85, v87
	v_add_f32_e32 v84, 1.0, v84
	v_mul_f32_e64 v87, |v85|, s82
	ds_read_b128 v[168:171], v77 offset:704
	ds_read_b128 v[172:175], v77 offset:720
	v_log_f32_e32 v84, v84
	v_exp_f32_e32 v87, v87
	v_max_f32_e64 v83, -v83, 0
	v_max_f32_e64 v85, -v85, 0
	v_fmac_f32_e32 v83, 0x3f317218, v84
	v_add_f32_e32 v84, 1.0, v87
	s_waitcnt lgkmcnt(13)
	v_mul_f32_e32 v87, v3, v121
	v_fmac_f32_e32 v87, v2, v120
	v_mul_f32_e32 v88, v5, v123
	v_fmac_f32_e32 v88, v4, v122
	v_add_f32_e32 v87, v87, v88
	s_waitcnt lgkmcnt(12)
	v_mul_f32_e32 v93, v7, v125
	ds_read_b128 v[176:179], v77 offset:736
	v_fmac_f32_e32 v93, v6, v124
	v_mul_f32_e32 v92, v9, v127
	v_fmac_f32_e32 v92, v8, v126
	v_add_f32_e32 v87, v79, v87
	v_add_f32_e32 v92, v93, v92
	v_add_f32_e32 v87, v87, v92
	ds_read_b128 v[180:183], v77 offset:752
	s_waitcnt lgkmcnt(13)
	v_mul_f32_e32 v89, v11, v129
	v_fmac_f32_e32 v89, v10, v128
	v_mul_f32_e32 v88, v13, v131
	v_fmac_f32_e32 v88, v12, v130
	v_add_f32_e32 v88, v89, v88
	v_add_f32_e32 v87, v87, v88
	s_waitcnt lgkmcnt(12)
	v_mul_f32_e32 v88, v15, v133
	v_mul_f32_e32 v89, v17, v135
	v_fmac_f32_e32 v88, v14, v132
	v_fmac_f32_e32 v89, v16, v134
	v_add_f32_e32 v88, v88, v89
	v_add_f32_e32 v87, v87, v88
	v_mul_f32_e64 v88, |v87|, s82
	v_log_f32_e32 v84, v84
	v_exp_f32_e32 v92, v88
	ds_read_b128 v[120:123], v77 offset:768
	v_max_f32_e64 v87, -v87, 0
	v_fmac_f32_e32 v85, 0x3f317218, v84
	v_add_f32_e32 v84, 1.0, v92
	ds_read_b128 v[124:127], v77 offset:784
	s_waitcnt lgkmcnt(13)
	v_mul_f32_e32 v89, v3, v137
	v_fmac_f32_e32 v89, v2, v136
	v_mul_f32_e32 v88, v5, v139
	v_fmac_f32_e32 v88, v4, v138
	v_add_f32_e32 v88, v89, v88
	s_waitcnt lgkmcnt(12)
	v_mul_f32_e32 v93, v7, v141
	v_add_f32_e32 v96, v79, v88
	v_fmac_f32_e32 v93, v6, v140
	v_mul_f32_e32 v92, v9, v143
	ds_read_b128 v[128:131], v77 offset:800
	v_fmac_f32_e32 v92, v8, v142
	v_add_f32_e32 v92, v93, v92
	v_add_f32_e32 v96, v96, v92
	ds_read_b128 v[132:135], v77 offset:816
	s_waitcnt lgkmcnt(13)
	v_mul_f32_e32 v89, v11, v145
	v_fmac_f32_e32 v89, v10, v144
	v_mul_f32_e32 v88, v13, v147
	v_fmac_f32_e32 v88, v12, v146
	v_add_f32_e32 v88, v89, v88
	s_waitcnt lgkmcnt(12)
	v_mul_f32_e32 v89, v15, v149
	v_mul_f32_e32 v90, v17, v151
	v_fmac_f32_e32 v89, v14, v148
	v_fmac_f32_e32 v90, v16, v150
	v_add_f32_e32 v88, v96, v88
	v_add_f32_e32 v89, v89, v90
	v_add_f32_e32 v92, v88, v89
	v_mul_f32_e64 v88, |v92|, s82
	v_log_f32_e32 v84, v84
	v_exp_f32_e32 v88, v88
	v_fmamk_f32 v83, v83, 0xbd800000, v82
	v_fmamk_f32 v85, v85, 0xbd800000, v83
	v_fmac_f32_e32 v87, 0x3f317218, v84
	v_add_f32_e32 v84, 1.0, v88
	v_log_f32_e32 v93, v84
	ds_read_b128 v[136:139], v77 offset:832
	v_fmamk_f32 v84, v87, 0xbd800000, v85
	v_max_f32_e64 v87, -v92, 0
	v_fmac_f32_e32 v87, 0x3f317218, v93
	ds_read_b128 v[140:143], v77 offset:848
	s_waitcnt lgkmcnt(13)
	v_mul_f32_e32 v89, v3, v153
	v_fmac_f32_e32 v89, v2, v152
	v_mul_f32_e32 v88, v5, v155
	v_fmac_f32_e32 v88, v4, v154
	v_add_f32_e32 v88, v89, v88
	s_waitcnt lgkmcnt(12)
	v_mul_f32_e32 v93, v7, v157
	v_add_f32_e32 v96, v79, v88
	v_fmac_f32_e32 v93, v6, v156
	v_mul_f32_e32 v92, v9, v159
	ds_read_b128 v[144:147], v77 offset:864
	v_fmac_f32_e32 v92, v8, v158
	v_add_f32_e32 v92, v93, v92
	v_add_f32_e32 v96, v96, v92
	ds_read_b128 v[148:151], v77 offset:880
	s_waitcnt lgkmcnt(13)
	v_mul_f32_e32 v89, v11, v161
	v_fmac_f32_e32 v89, v10, v160
	v_mul_f32_e32 v88, v13, v163
	v_fmac_f32_e32 v88, v12, v162
	v_add_f32_e32 v88, v89, v88
	s_waitcnt lgkmcnt(12)
	v_mul_f32_e32 v89, v15, v165
	v_mul_f32_e32 v90, v17, v167
	v_fmac_f32_e32 v89, v14, v164
	v_fmac_f32_e32 v90, v16, v166
	v_add_f32_e32 v88, v96, v88
	v_add_f32_e32 v89, v89, v90
	v_add_f32_e32 v92, v88, v89
	v_mul_f32_e64 v88, |v92|, s82
	v_exp_f32_e32 v93, v88
	ds_read_b128 v[152:155], v77 offset:896
	v_max_f32_e64 v96, -v92, 0
	v_fmamk_f32 v87, v87, 0xbd800000, v84
	v_add_f32_e32 v92, 1.0, v93
	v_log_f32_e32 v97, v92
	ds_read_b128 v[156:159], v77 offset:912
	s_waitcnt lgkmcnt(13)
	v_mul_f32_e32 v89, v3, v169
	v_fmac_f32_e32 v89, v2, v168
	v_mul_f32_e32 v88, v5, v171
	v_fmac_f32_e32 v88, v4, v170
	v_add_f32_e32 v88, v89, v88
	s_waitcnt lgkmcnt(12)
	v_mul_f32_e32 v93, v7, v173
	v_add_f32_e32 v98, v79, v88
	v_fmac_f32_e32 v93, v6, v172
	v_mul_f32_e32 v92, v9, v175
	ds_read_b128 v[160:163], v77 offset:928
	v_fmac_f32_e32 v92, v8, v174
	v_add_f32_e32 v92, v93, v92
	v_add_f32_e32 v98, v98, v92
	ds_read_b128 v[164:167], v77 offset:944
	s_waitcnt lgkmcnt(13)
	v_mul_f32_e32 v89, v11, v177
	v_fmac_f32_e32 v89, v10, v176
	v_mul_f32_e32 v88, v13, v179
	v_fmac_f32_e32 v88, v12, v178
	v_add_f32_e32 v88, v89, v88
	s_waitcnt lgkmcnt(12)
	v_mul_f32_e32 v89, v15, v181
	v_mul_f32_e32 v90, v17, v183
	v_fmac_f32_e32 v89, v14, v180
	v_fmac_f32_e32 v90, v16, v182
	v_add_f32_e32 v88, v98, v88
	v_add_f32_e32 v89, v89, v90
	v_add_f32_e32 v89, v88, v89
	v_mul_f32_e64 v88, |v89|, s82
	v_exp_f32_e32 v94, v88
	ds_read_b128 v[168:171], v77 offset:960
	v_fmac_f32_e32 v96, 0x3f317218, v97
	v_fmamk_f32 v88, v96, 0xbd800000, v87
	v_add_f32_e32 v94, 1.0, v94
	v_log_f32_e32 v98, v94
	ds_read_b128 v[172:175], v77 offset:976
	s_waitcnt lgkmcnt(13)
	v_mul_f32_e32 v91, v3, v121
	v_fmac_f32_e32 v91, v2, v120
	v_mul_f32_e32 v90, v5, v123
	v_fmac_f32_e32 v90, v4, v122
	v_add_f32_e32 v90, v91, v90
	s_waitcnt lgkmcnt(12)
	v_mul_f32_e32 v95, v7, v125
	v_add_f32_e32 v99, v79, v90
	v_fmac_f32_e32 v95, v6, v124
	v_mul_f32_e32 v94, v9, v127
	ds_read_b128 v[176:179], v77 offset:992
	v_fmac_f32_e32 v94, v8, v126
	v_add_f32_e32 v94, v95, v94
	v_add_f32_e32 v99, v99, v94
	ds_read_b128 v[180:183], v77 offset:1008
	s_waitcnt lgkmcnt(13)
	v_mul_f32_e32 v91, v11, v129
	v_fmac_f32_e32 v91, v10, v128
	v_mul_f32_e32 v90, v13, v131
	v_fmac_f32_e32 v90, v12, v130
	v_add_f32_e32 v90, v91, v90
	s_waitcnt lgkmcnt(12)
	v_mul_f32_e32 v91, v15, v133
	v_mul_f32_e32 v92, v17, v135
	v_fmac_f32_e32 v91, v14, v132
	v_fmac_f32_e32 v92, v16, v134
	v_add_f32_e32 v90, v99, v90
	v_add_f32_e32 v91, v91, v92
	v_add_f32_e32 v99, v90, v91
	v_mul_f32_e64 v90, |v99|, s82
	v_exp_f32_e32 v94, v90
	ds_read_b128 v[120:123], v77 offset:1024
	v_max_f32_e64 v89, -v89, 0
	v_fmac_f32_e32 v89, 0x3f317218, v98
	v_add_f32_e32 v94, 1.0, v94
	v_log_f32_e32 v98, v94
	ds_read_b128 v[124:127], v77 offset:1040
	s_waitcnt lgkmcnt(13)
	v_mul_f32_e32 v91, v3, v137
	v_fmac_f32_e32 v91, v2, v136
	v_mul_f32_e32 v90, v5, v139
	v_fmac_f32_e32 v90, v4, v138
	v_add_f32_e32 v90, v91, v90
	s_waitcnt lgkmcnt(12)
	v_mul_f32_e32 v95, v7, v141
	v_add_f32_e32 v100, v79, v90
	v_fmac_f32_e32 v95, v6, v140
	v_mul_f32_e32 v94, v9, v143
	ds_read_b128 v[128:131], v77 offset:1056
	v_fmac_f32_e32 v94, v8, v142
	v_add_f32_e32 v94, v95, v94
	v_add_f32_e32 v100, v100, v94
	ds_read_b128 v[132:135], v77 offset:1072
	s_waitcnt lgkmcnt(13)
	v_mul_f32_e32 v91, v11, v145
	v_fmac_f32_e32 v91, v10, v144
	v_mul_f32_e32 v90, v13, v147
	v_fmac_f32_e32 v90, v12, v146
	v_add_f32_e32 v90, v91, v90
	s_waitcnt lgkmcnt(12)
	v_mul_f32_e32 v91, v15, v149
	v_mul_f32_e32 v92, v17, v151
	v_fmac_f32_e32 v91, v14, v148
	v_fmac_f32_e32 v92, v16, v150
	v_add_f32_e32 v90, v100, v90
	v_add_f32_e32 v91, v91, v92
	v_add_f32_e32 v91, v90, v91
	v_mul_f32_e64 v90, |v91|, s82
	v_exp_f32_e32 v92, v90
	v_fmamk_f32 v90, v89, 0xbd800000, v88
	v_max_f32_e64 v89, -v99, 0
	v_max_f32_e64 v91, -v91, 0
	v_add_f32_e32 v92, 1.0, v92
	v_log_f32_e32 v96, v92
	ds_read_b128 v[136:139], v77 offset:1088
	v_fmac_f32_e32 v89, 0x3f317218, v98
	v_fmamk_f32 v89, v89, 0xbd800000, v90
	v_fmac_f32_e32 v91, 0x3f317218, v96
	ds_read_b128 v[140:143], v77 offset:1104
	s_waitcnt lgkmcnt(13)
	v_mul_f32_e32 v93, v3, v153
	v_fmac_f32_e32 v93, v2, v152
	v_mul_f32_e32 v92, v5, v155
	v_fmac_f32_e32 v92, v4, v154
	v_add_f32_e32 v92, v93, v92
	s_waitcnt lgkmcnt(12)
	v_mul_f32_e32 v97, v7, v157
	v_add_f32_e32 v100, v79, v92
	v_fmac_f32_e32 v97, v6, v156
	v_mul_f32_e32 v96, v9, v159
	ds_read_b128 v[144:147], v77 offset:1120
	v_fmac_f32_e32 v96, v8, v158
	v_add_f32_e32 v96, v97, v96
	v_add_f32_e32 v100, v100, v96
	ds_read_b128 v[148:151], v77 offset:1136
	s_waitcnt lgkmcnt(13)
	v_mul_f32_e32 v93, v11, v161
	v_fmac_f32_e32 v93, v10, v160
	v_mul_f32_e32 v92, v13, v163
	v_fmac_f32_e32 v92, v12, v162
	v_add_f32_e32 v92, v93, v92
	s_waitcnt lgkmcnt(12)
	v_mul_f32_e32 v93, v15, v165
	v_mul_f32_e32 v94, v17, v167
	v_fmac_f32_e32 v93, v14, v164
	v_fmac_f32_e32 v94, v16, v166
	v_add_f32_e32 v92, v100, v92
	v_add_f32_e32 v93, v93, v94
	v_add_f32_e32 v96, v92, v93
	v_mul_f32_e64 v92, |v96|, s82
	v_exp_f32_e32 v97, v92
	ds_read_b128 v[152:155], v77 offset:1152
	v_max_f32_e64 v100, -v96, 0
	v_fmamk_f32 v91, v91, 0xbd800000, v89
	v_add_f32_e32 v96, 1.0, v97
	v_log_f32_e32 v101, v96
	ds_read_b128 v[156:159], v77 offset:1168
	s_waitcnt lgkmcnt(13)
	v_mul_f32_e32 v93, v3, v169
	v_fmac_f32_e32 v93, v2, v168
	v_mul_f32_e32 v92, v5, v171
	v_fmac_f32_e32 v92, v4, v170
	v_add_f32_e32 v92, v93, v92
	s_waitcnt lgkmcnt(12)
	v_mul_f32_e32 v97, v7, v173
	v_add_f32_e32 v102, v79, v92
	v_fmac_f32_e32 v97, v6, v172
	v_mul_f32_e32 v96, v9, v175
	ds_read_b128 v[160:163], v77 offset:1184
	v_fmac_f32_e32 v96, v8, v174
	v_add_f32_e32 v96, v97, v96
	v_add_f32_e32 v102, v102, v96
	ds_read_b128 v[164:167], v77 offset:1200
	s_waitcnt lgkmcnt(13)
	v_mul_f32_e32 v93, v11, v177
	v_fmac_f32_e32 v93, v10, v176
	v_mul_f32_e32 v92, v13, v179
	v_fmac_f32_e32 v92, v12, v178
	v_add_f32_e32 v92, v93, v92
	s_waitcnt lgkmcnt(12)
	v_mul_f32_e32 v93, v15, v181
	v_mul_f32_e32 v94, v17, v183
	v_fmac_f32_e32 v93, v14, v180
	v_fmac_f32_e32 v94, v16, v182
	v_add_f32_e32 v92, v102, v92
	v_add_f32_e32 v93, v93, v94
	v_add_f32_e32 v93, v92, v93
	v_mul_f32_e64 v92, |v93|, s82
	v_exp_f32_e32 v98, v92
	ds_read_b128 v[168:171], v77 offset:1216
	v_fmac_f32_e32 v100, 0x3f317218, v101
	v_fmamk_f32 v92, v100, 0xbd800000, v91
	v_add_f32_e32 v98, 1.0, v98
	v_log_f32_e32 v102, v98
	ds_read_b128 v[172:175], v77 offset:1232
	s_waitcnt lgkmcnt(13)
	v_mul_f32_e32 v95, v3, v121
	v_fmac_f32_e32 v95, v2, v120
	v_mul_f32_e32 v94, v5, v123
	v_fmac_f32_e32 v94, v4, v122
	v_add_f32_e32 v94, v95, v94
	s_waitcnt lgkmcnt(12)
	v_mul_f32_e32 v99, v7, v125
	v_add_f32_e32 v103, v79, v94
	v_fmac_f32_e32 v99, v6, v124
	v_mul_f32_e32 v98, v9, v127
	ds_read_b128 v[176:179], v77 offset:1248
	v_fmac_f32_e32 v98, v8, v126
	v_add_f32_e32 v98, v99, v98
	v_add_f32_e32 v103, v103, v98
	ds_read_b128 v[180:183], v77 offset:1264
	s_waitcnt lgkmcnt(13)
	v_mul_f32_e32 v95, v11, v129
	v_fmac_f32_e32 v95, v10, v128
	v_mul_f32_e32 v94, v13, v131
	v_fmac_f32_e32 v94, v12, v130
	v_add_f32_e32 v94, v95, v94
	s_waitcnt lgkmcnt(12)
	v_mul_f32_e32 v95, v15, v133
	v_mul_f32_e32 v96, v17, v135
	v_fmac_f32_e32 v95, v14, v132
	v_fmac_f32_e32 v96, v16, v134
	v_add_f32_e32 v94, v103, v94
	v_add_f32_e32 v95, v95, v96
	v_add_f32_e32 v103, v94, v95
	v_mul_f32_e64 v94, |v103|, s82
	v_exp_f32_e32 v98, v94
	ds_read_b128 v[120:123], v77 offset:1280
	v_max_f32_e64 v93, -v93, 0
	v_fmac_f32_e32 v93, 0x3f317218, v102
	v_add_f32_e32 v98, 1.0, v98
	v_log_f32_e32 v102, v98
	ds_read_b128 v[124:127], v77 offset:1296
	s_waitcnt lgkmcnt(13)
	v_mul_f32_e32 v95, v3, v137
	v_fmac_f32_e32 v95, v2, v136
	v_mul_f32_e32 v94, v5, v139
	v_fmac_f32_e32 v94, v4, v138
	v_add_f32_e32 v94, v95, v94
	s_waitcnt lgkmcnt(12)
	v_mul_f32_e32 v99, v7, v141
	v_add_f32_e32 v104, v79, v94
	v_fmac_f32_e32 v99, v6, v140
	v_mul_f32_e32 v98, v9, v143
	ds_read_b128 v[128:131], v77 offset:1312
	v_fmac_f32_e32 v98, v8, v142
	v_add_f32_e32 v98, v99, v98
	v_add_f32_e32 v104, v104, v98
	ds_read_b128 v[132:135], v77 offset:1328
	s_waitcnt lgkmcnt(13)
	v_mul_f32_e32 v95, v11, v145
	v_fmac_f32_e32 v95, v10, v144
	v_mul_f32_e32 v94, v13, v147
	v_fmac_f32_e32 v94, v12, v146
	v_add_f32_e32 v94, v95, v94
	s_waitcnt lgkmcnt(12)
	v_mul_f32_e32 v95, v15, v149
	v_mul_f32_e32 v96, v17, v151
	v_fmac_f32_e32 v95, v14, v148
	v_fmac_f32_e32 v96, v16, v150
	v_add_f32_e32 v94, v104, v94
	v_add_f32_e32 v95, v95, v96
	v_add_f32_e32 v95, v94, v95
	v_mul_f32_e64 v94, |v95|, s82
	v_exp_f32_e32 v96, v94
	v_fmamk_f32 v94, v93, 0xbd800000, v92
	v_max_f32_e64 v93, -v103, 0
	v_max_f32_e64 v95, -v95, 0
	v_add_f32_e32 v96, 1.0, v96
	v_log_f32_e32 v100, v96
	ds_read_b128 v[136:139], v77 offset:1344
	v_fmac_f32_e32 v93, 0x3f317218, v102
	v_fmamk_f32 v93, v93, 0xbd800000, v94
	v_fmac_f32_e32 v95, 0x3f317218, v100
	ds_read_b128 v[140:143], v77 offset:1360
	s_waitcnt lgkmcnt(13)
	v_mul_f32_e32 v97, v3, v153
	v_fmac_f32_e32 v97, v2, v152
	v_mul_f32_e32 v96, v5, v155
	v_fmac_f32_e32 v96, v4, v154
	v_add_f32_e32 v96, v97, v96
	s_waitcnt lgkmcnt(12)
	v_mul_f32_e32 v101, v7, v157
	v_add_f32_e32 v104, v79, v96
	v_fmac_f32_e32 v101, v6, v156
	v_mul_f32_e32 v100, v9, v159
	ds_read_b128 v[144:147], v77 offset:1376
	v_fmac_f32_e32 v100, v8, v158
	v_add_f32_e32 v100, v101, v100
	v_add_f32_e32 v104, v104, v100
	ds_read_b128 v[148:151], v77 offset:1392
	s_waitcnt lgkmcnt(13)
	v_mul_f32_e32 v97, v11, v161
	v_fmac_f32_e32 v97, v10, v160
	v_mul_f32_e32 v96, v13, v163
	v_fmac_f32_e32 v96, v12, v162
	v_add_f32_e32 v96, v97, v96
	s_waitcnt lgkmcnt(12)
	v_mul_f32_e32 v97, v15, v165
	v_mul_f32_e32 v98, v17, v167
	v_fmac_f32_e32 v97, v14, v164
	v_fmac_f32_e32 v98, v16, v166
	v_add_f32_e32 v96, v104, v96
	v_add_f32_e32 v97, v97, v98
	v_add_f32_e32 v100, v96, v97
	v_mul_f32_e64 v96, |v100|, s82
	v_exp_f32_e32 v101, v96
	ds_read_b128 v[152:155], v77 offset:1408
	v_max_f32_e64 v104, -v100, 0
	v_fmamk_f32 v95, v95, 0xbd800000, v93
	v_add_f32_e32 v100, 1.0, v101
	v_log_f32_e32 v105, v100
	ds_read_b128 v[156:159], v77 offset:1424
	s_waitcnt lgkmcnt(13)
	v_mul_f32_e32 v97, v3, v169
	v_fmac_f32_e32 v97, v2, v168
	v_mul_f32_e32 v96, v5, v171
	v_fmac_f32_e32 v96, v4, v170
	v_add_f32_e32 v96, v97, v96
	s_waitcnt lgkmcnt(12)
	v_mul_f32_e32 v101, v7, v173
	v_add_f32_e32 v106, v79, v96
	v_fmac_f32_e32 v101, v6, v172
	v_mul_f32_e32 v100, v9, v175
	ds_read_b128 v[160:163], v77 offset:1440
	v_fmac_f32_e32 v100, v8, v174
	v_add_f32_e32 v100, v101, v100
	v_add_f32_e32 v106, v106, v100
	ds_read_b128 v[164:167], v77 offset:1456
	s_waitcnt lgkmcnt(13)
	v_mul_f32_e32 v97, v11, v177
	v_fmac_f32_e32 v97, v10, v176
	v_mul_f32_e32 v96, v13, v179
	v_fmac_f32_e32 v96, v12, v178
	v_add_f32_e32 v96, v97, v96
	s_waitcnt lgkmcnt(12)
	v_mul_f32_e32 v97, v15, v181
	v_mul_f32_e32 v98, v17, v183
	v_fmac_f32_e32 v97, v14, v180
	v_fmac_f32_e32 v98, v16, v182
	v_add_f32_e32 v96, v106, v96
	v_add_f32_e32 v97, v97, v98
	v_add_f32_e32 v97, v96, v97
	v_mul_f32_e64 v96, |v97|, s82
	v_exp_f32_e32 v102, v96
	ds_read_b128 v[168:171], v77 offset:1472
	v_fmac_f32_e32 v104, 0x3f317218, v105
	v_fmamk_f32 v96, v104, 0xbd800000, v95
	v_add_f32_e32 v102, 1.0, v102
	v_log_f32_e32 v106, v102
	ds_read_b128 v[172:175], v77 offset:1488
	s_waitcnt lgkmcnt(13)
	v_mul_f32_e32 v99, v3, v121
	v_fmac_f32_e32 v99, v2, v120
	v_mul_f32_e32 v98, v5, v123
	v_fmac_f32_e32 v98, v4, v122
	v_add_f32_e32 v98, v99, v98
	s_waitcnt lgkmcnt(12)
	v_mul_f32_e32 v103, v7, v125
	v_add_f32_e32 v107, v79, v98
	v_fmac_f32_e32 v103, v6, v124
	v_mul_f32_e32 v102, v9, v127
	ds_read_b128 v[176:179], v77 offset:1504
	v_fmac_f32_e32 v102, v8, v126
	v_add_f32_e32 v102, v103, v102
	v_add_f32_e32 v107, v107, v102
	ds_read_b128 v[180:183], v77 offset:1520
	s_waitcnt lgkmcnt(13)
	v_mul_f32_e32 v99, v11, v129
	v_fmac_f32_e32 v99, v10, v128
	v_mul_f32_e32 v98, v13, v131
	v_fmac_f32_e32 v98, v12, v130
	v_add_f32_e32 v98, v99, v98
	s_waitcnt lgkmcnt(12)
	v_mul_f32_e32 v99, v15, v133
	v_mul_f32_e32 v100, v17, v135
	v_fmac_f32_e32 v99, v14, v132
	v_fmac_f32_e32 v100, v16, v134
	v_add_f32_e32 v98, v107, v98
	v_add_f32_e32 v99, v99, v100
	v_add_f32_e32 v107, v98, v99
	v_mul_f32_e64 v98, |v107|, s82
	v_exp_f32_e32 v102, v98
	ds_read_b128 v[120:123], v77 offset:1536
	v_max_f32_e64 v97, -v97, 0
	v_fmac_f32_e32 v97, 0x3f317218, v106
	v_add_f32_e32 v102, 1.0, v102
	v_log_f32_e32 v106, v102
	ds_read_b128 v[124:127], v77 offset:1552
	s_waitcnt lgkmcnt(13)
	v_mul_f32_e32 v99, v3, v137
	v_fmac_f32_e32 v99, v2, v136
	v_mul_f32_e32 v98, v5, v139
	v_fmac_f32_e32 v98, v4, v138
	v_add_f32_e32 v98, v99, v98
	s_waitcnt lgkmcnt(12)
	v_mul_f32_e32 v103, v7, v141
	v_add_f32_e32 v108, v79, v98
	v_fmac_f32_e32 v103, v6, v140
	v_mul_f32_e32 v102, v9, v143
	ds_read_b128 v[128:131], v77 offset:1568
	v_fmac_f32_e32 v102, v8, v142
	v_add_f32_e32 v102, v103, v102
	v_add_f32_e32 v108, v108, v102
	ds_read_b128 v[132:135], v77 offset:1584
	s_waitcnt lgkmcnt(13)
	v_mul_f32_e32 v99, v11, v145
	v_fmac_f32_e32 v99, v10, v144
	v_mul_f32_e32 v98, v13, v147
	v_fmac_f32_e32 v98, v12, v146
	v_add_f32_e32 v98, v99, v98
	s_waitcnt lgkmcnt(12)
	v_mul_f32_e32 v99, v15, v149
	v_mul_f32_e32 v100, v17, v151
	v_fmac_f32_e32 v99, v14, v148
	v_fmac_f32_e32 v100, v16, v150
	v_add_f32_e32 v98, v108, v98
	v_add_f32_e32 v99, v99, v100
	v_add_f32_e32 v99, v98, v99
	v_mul_f32_e64 v98, |v99|, s82
	v_exp_f32_e32 v100, v98
	v_fmamk_f32 v98, v97, 0xbd800000, v96
	v_max_f32_e64 v97, -v107, 0
	v_max_f32_e64 v99, -v99, 0
	v_add_f32_e32 v100, 1.0, v100
	v_log_f32_e32 v104, v100
	ds_read_b128 v[136:139], v77 offset:1600
	v_fmac_f32_e32 v97, 0x3f317218, v106
	v_fmamk_f32 v97, v97, 0xbd800000, v98
	v_fmac_f32_e32 v99, 0x3f317218, v104
	ds_read_b128 v[140:143], v77 offset:1616
	s_waitcnt lgkmcnt(13)
	v_mul_f32_e32 v101, v3, v153
	v_fmac_f32_e32 v101, v2, v152
	v_mul_f32_e32 v100, v5, v155
	v_fmac_f32_e32 v100, v4, v154
	v_add_f32_e32 v100, v101, v100
	s_waitcnt lgkmcnt(12)
	v_mul_f32_e32 v105, v7, v157
	v_add_f32_e32 v108, v79, v100
	v_fmac_f32_e32 v105, v6, v156
	v_mul_f32_e32 v104, v9, v159
	ds_read_b128 v[144:147], v77 offset:1632
	v_fmac_f32_e32 v104, v8, v158
	v_add_f32_e32 v104, v105, v104
	v_add_f32_e32 v108, v108, v104
	ds_read_b128 v[148:151], v77 offset:1648
	s_waitcnt lgkmcnt(13)
	v_mul_f32_e32 v101, v11, v161
	v_fmac_f32_e32 v101, v10, v160
	v_mul_f32_e32 v100, v13, v163
	v_fmac_f32_e32 v100, v12, v162
	v_add_f32_e32 v100, v101, v100
	s_waitcnt lgkmcnt(12)
	v_mul_f32_e32 v101, v15, v165
	v_mul_f32_e32 v102, v17, v167
	v_fmac_f32_e32 v101, v14, v164
	v_fmac_f32_e32 v102, v16, v166
	v_add_f32_e32 v100, v108, v100
	v_add_f32_e32 v101, v101, v102
	v_add_f32_e32 v104, v100, v101
	v_mul_f32_e64 v100, |v104|, s82
	v_exp_f32_e32 v105, v100
	ds_read_b128 v[152:155], v77 offset:1664
	v_max_f32_e64 v108, -v104, 0
	v_fmamk_f32 v99, v99, 0xbd800000, v97
	v_add_f32_e32 v104, 1.0, v105
	v_log_f32_e32 v109, v104
	ds_read_b128 v[156:159], v77 offset:1680
	s_waitcnt lgkmcnt(13)
	v_mul_f32_e32 v101, v3, v169
	v_fmac_f32_e32 v101, v2, v168
	v_mul_f32_e32 v100, v5, v171
	v_fmac_f32_e32 v100, v4, v170
	v_add_f32_e32 v100, v101, v100
	s_waitcnt lgkmcnt(12)
	v_mul_f32_e32 v105, v7, v173
	v_add_f32_e32 v110, v79, v100
	v_fmac_f32_e32 v105, v6, v172
	v_mul_f32_e32 v104, v9, v175
	ds_read_b128 v[160:163], v77 offset:1696
	v_fmac_f32_e32 v104, v8, v174
	v_add_f32_e32 v104, v105, v104
	v_add_f32_e32 v110, v110, v104
	ds_read_b128 v[164:167], v77 offset:1712
	s_waitcnt lgkmcnt(13)
	v_mul_f32_e32 v101, v11, v177
	v_fmac_f32_e32 v101, v10, v176
	v_mul_f32_e32 v100, v13, v179
	v_fmac_f32_e32 v100, v12, v178
	v_add_f32_e32 v100, v101, v100
	s_waitcnt lgkmcnt(12)
	v_mul_f32_e32 v101, v15, v181
	v_mul_f32_e32 v102, v17, v183
	v_fmac_f32_e32 v101, v14, v180
	v_fmac_f32_e32 v102, v16, v182
	v_add_f32_e32 v100, v110, v100
	v_add_f32_e32 v101, v101, v102
	v_add_f32_e32 v101, v100, v101
	v_mul_f32_e64 v100, |v101|, s82
	v_exp_f32_e32 v106, v100
	ds_read_b128 v[168:171], v77 offset:1728
	v_fmac_f32_e32 v108, 0x3f317218, v109
	v_fmamk_f32 v100, v108, 0xbd800000, v99
	v_add_f32_e32 v106, 1.0, v106
	v_log_f32_e32 v110, v106
	ds_read_b128 v[172:175], v77 offset:1744
	s_waitcnt lgkmcnt(13)
	v_mul_f32_e32 v103, v3, v121
	v_fmac_f32_e32 v103, v2, v120
	v_mul_f32_e32 v102, v5, v123
	v_fmac_f32_e32 v102, v4, v122
	v_add_f32_e32 v102, v103, v102
	s_waitcnt lgkmcnt(12)
	v_mul_f32_e32 v107, v7, v125
	v_add_f32_e32 v111, v79, v102
	v_fmac_f32_e32 v107, v6, v124
	v_mul_f32_e32 v106, v9, v127
	ds_read_b128 v[176:179], v77 offset:1760
	v_fmac_f32_e32 v106, v8, v126
	v_add_f32_e32 v106, v107, v106
	v_add_f32_e32 v111, v111, v106
	ds_read_b128 v[180:183], v77 offset:1776
	s_waitcnt lgkmcnt(13)
	v_mul_f32_e32 v103, v11, v129
	v_fmac_f32_e32 v103, v10, v128
	v_mul_f32_e32 v102, v13, v131
	v_fmac_f32_e32 v102, v12, v130
	v_add_f32_e32 v102, v103, v102
	s_waitcnt lgkmcnt(12)
	v_mul_f32_e32 v103, v15, v133
	v_mul_f32_e32 v104, v17, v135
	v_fmac_f32_e32 v103, v14, v132
	v_fmac_f32_e32 v104, v16, v134
	v_add_f32_e32 v102, v111, v102
	v_add_f32_e32 v103, v103, v104
	v_add_f32_e32 v111, v102, v103
	v_mul_f32_e64 v102, |v111|, s82
	v_exp_f32_e32 v106, v102
	ds_read_b128 v[120:123], v77 offset:1792
	v_max_f32_e64 v101, -v101, 0
	v_fmac_f32_e32 v101, 0x3f317218, v110
	v_add_f32_e32 v106, 1.0, v106
	v_log_f32_e32 v110, v106
	ds_read_b128 v[124:127], v77 offset:1808
	s_waitcnt lgkmcnt(13)
	v_mul_f32_e32 v103, v3, v137
	v_fmac_f32_e32 v103, v2, v136
	v_mul_f32_e32 v102, v5, v139
	v_fmac_f32_e32 v102, v4, v138
	v_add_f32_e32 v102, v103, v102
	s_waitcnt lgkmcnt(12)
	v_mul_f32_e32 v107, v7, v141
	v_add_f32_e32 v112, v79, v102
	v_fmac_f32_e32 v107, v6, v140
	v_mul_f32_e32 v106, v9, v143
	ds_read_b128 v[128:131], v77 offset:1824
	v_fmac_f32_e32 v106, v8, v142
	v_add_f32_e32 v106, v107, v106
	v_add_f32_e32 v112, v112, v106
	ds_read_b128 v[132:135], v77 offset:1840
	s_waitcnt lgkmcnt(13)
	v_mul_f32_e32 v103, v11, v145
	v_fmac_f32_e32 v103, v10, v144
	v_mul_f32_e32 v102, v13, v147
	v_fmac_f32_e32 v102, v12, v146
	v_add_f32_e32 v102, v103, v102
	s_waitcnt lgkmcnt(12)
	v_mul_f32_e32 v103, v15, v149
	v_mul_f32_e32 v104, v17, v151
	v_fmac_f32_e32 v103, v14, v148
	v_fmac_f32_e32 v104, v16, v150
	v_add_f32_e32 v102, v112, v102
	v_add_f32_e32 v103, v103, v104
	v_add_f32_e32 v103, v102, v103
	v_mul_f32_e64 v102, |v103|, s82
	v_exp_f32_e32 v104, v102
	v_fmamk_f32 v102, v101, 0xbd800000, v100
	v_max_f32_e64 v101, -v111, 0
	v_max_f32_e64 v103, -v103, 0
	v_add_f32_e32 v104, 1.0, v104
	v_log_f32_e32 v108, v104
	ds_read_b128 v[136:139], v77 offset:1856
	v_fmac_f32_e32 v101, 0x3f317218, v110
	v_fmamk_f32 v101, v101, 0xbd800000, v102
	v_fmac_f32_e32 v103, 0x3f317218, v108
	ds_read_b128 v[140:143], v77 offset:1872
	s_waitcnt lgkmcnt(13)
	v_mul_f32_e32 v105, v3, v153
	v_fmac_f32_e32 v105, v2, v152
	v_mul_f32_e32 v104, v5, v155
	v_fmac_f32_e32 v104, v4, v154
	v_add_f32_e32 v104, v105, v104
	s_waitcnt lgkmcnt(12)
	v_mul_f32_e32 v109, v7, v157
	v_add_f32_e32 v112, v79, v104
	v_fmac_f32_e32 v109, v6, v156
	v_mul_f32_e32 v108, v9, v159
	ds_read_b128 v[144:147], v77 offset:1888
	v_fmac_f32_e32 v108, v8, v158
	v_add_f32_e32 v108, v109, v108
	v_add_f32_e32 v112, v112, v108
	ds_read_b128 v[148:151], v77 offset:1904
	s_waitcnt lgkmcnt(13)
	v_mul_f32_e32 v105, v11, v161
	v_fmac_f32_e32 v105, v10, v160
	v_mul_f32_e32 v104, v13, v163
	v_fmac_f32_e32 v104, v12, v162
	v_add_f32_e32 v104, v105, v104
	s_waitcnt lgkmcnt(12)
	v_mul_f32_e32 v105, v15, v165
	v_mul_f32_e32 v106, v17, v167
	v_fmac_f32_e32 v105, v14, v164
	v_fmac_f32_e32 v106, v16, v166
	v_add_f32_e32 v104, v112, v104
	v_add_f32_e32 v105, v105, v106
	v_add_f32_e32 v108, v104, v105
	v_mul_f32_e64 v104, |v108|, s82
	v_exp_f32_e32 v109, v104
	ds_read_b128 v[152:155], v77 offset:1920
	v_max_f32_e64 v112, -v108, 0
	v_fmamk_f32 v103, v103, 0xbd800000, v101
	v_add_f32_e32 v108, 1.0, v109
	v_log_f32_e32 v113, v108
	ds_read_b128 v[156:159], v77 offset:1936
	s_waitcnt lgkmcnt(13)
	v_mul_f32_e32 v105, v3, v169
	v_fmac_f32_e32 v105, v2, v168
	v_mul_f32_e32 v104, v5, v171
	v_fmac_f32_e32 v104, v4, v170
	v_add_f32_e32 v104, v105, v104
	s_waitcnt lgkmcnt(12)
	v_mul_f32_e32 v109, v7, v173
	v_add_f32_e32 v114, v79, v104
	v_fmac_f32_e32 v109, v6, v172
	v_mul_f32_e32 v108, v9, v175
	ds_read_b128 v[160:163], v77 offset:1952
	v_fmac_f32_e32 v108, v8, v174
	v_add_f32_e32 v108, v109, v108
	v_add_f32_e32 v114, v114, v108
	ds_read_b128 v[164:167], v77 offset:1968
	s_waitcnt lgkmcnt(13)
	v_mul_f32_e32 v105, v11, v177
	v_fmac_f32_e32 v105, v10, v176
	v_mul_f32_e32 v104, v13, v179
	v_fmac_f32_e32 v104, v12, v178
	v_add_f32_e32 v104, v105, v104
	s_waitcnt lgkmcnt(12)
	v_mul_f32_e32 v105, v15, v181
	v_mul_f32_e32 v106, v17, v183
	v_fmac_f32_e32 v105, v14, v180
	v_fmac_f32_e32 v106, v16, v182
	v_add_f32_e32 v104, v114, v104
	v_add_f32_e32 v105, v105, v106
	v_add_f32_e32 v105, v104, v105
	v_mul_f32_e64 v104, |v105|, s82
	v_exp_f32_e32 v110, v104
	ds_read_b128 v[168:171], v77 offset:1984
	v_fmac_f32_e32 v112, 0x3f317218, v113
	v_fmamk_f32 v104, v112, 0xbd800000, v103
	v_add_f32_e32 v110, 1.0, v110
	v_log_f32_e32 v114, v110
	ds_read_b128 v[172:175], v77 offset:2000
	s_waitcnt lgkmcnt(13)
	v_mul_f32_e32 v107, v3, v121
	v_fmac_f32_e32 v107, v2, v120
	v_mul_f32_e32 v106, v5, v123
	v_fmac_f32_e32 v106, v4, v122
	v_add_f32_e32 v106, v107, v106
	s_waitcnt lgkmcnt(12)
	v_mul_f32_e32 v111, v7, v125
	v_add_f32_e32 v115, v79, v106
	v_fmac_f32_e32 v111, v6, v124
	v_mul_f32_e32 v110, v9, v127
	ds_read_b128 v[176:179], v77 offset:2016
	v_fmac_f32_e32 v110, v8, v126
	v_add_f32_e32 v110, v111, v110
	v_add_f32_e32 v115, v115, v110
	ds_read_b128 v[180:183], v77 offset:2032
	s_waitcnt lgkmcnt(13)
	v_mul_f32_e32 v107, v11, v129
	v_fmac_f32_e32 v107, v10, v128
	v_mul_f32_e32 v106, v13, v131
	v_fmac_f32_e32 v106, v12, v130
	v_add_f32_e32 v106, v107, v106
	s_waitcnt lgkmcnt(12)
	v_mul_f32_e32 v107, v15, v133
	v_mul_f32_e32 v108, v17, v135
	v_fmac_f32_e32 v107, v14, v132
	v_fmac_f32_e32 v108, v16, v134
	v_add_f32_e32 v106, v115, v106
	v_add_f32_e32 v107, v107, v108
	v_add_f32_e32 v115, v106, v107
	v_mul_f32_e64 v106, |v115|, s82
	v_exp_f32_e32 v110, v106
	v_max_f32_e64 v105, -v105, 0
	v_fmac_f32_e32 v105, 0x3f317218, v114
	v_add_f32_e32 v110, 1.0, v110
	v_log_f32_e32 v114, v110
	s_waitcnt lgkmcnt(11)
	v_mul_f32_e32 v107, v3, v137
	v_fmac_f32_e32 v107, v2, v136
	v_mul_f32_e32 v106, v5, v139
	v_fmac_f32_e32 v106, v4, v138
	v_add_f32_e32 v106, v107, v106
	s_waitcnt lgkmcnt(10)
	v_mul_f32_e32 v111, v7, v141
	v_add_f32_e32 v116, v79, v106
	v_fmac_f32_e32 v111, v6, v140
	v_mul_f32_e32 v110, v9, v143
	v_fmac_f32_e32 v110, v8, v142
	v_add_f32_e32 v110, v111, v110
	v_add_f32_e32 v116, v116, v110
	s_waitcnt lgkmcnt(9)
	v_mul_f32_e32 v107, v11, v145
	v_fmac_f32_e32 v107, v10, v144
	v_mul_f32_e32 v106, v13, v147
	v_fmac_f32_e32 v106, v12, v146
	v_add_f32_e32 v106, v107, v106
	s_waitcnt lgkmcnt(8)
	v_mul_f32_e32 v107, v15, v149
	v_mul_f32_e32 v108, v17, v151
	v_fmac_f32_e32 v107, v14, v148
	v_fmac_f32_e32 v108, v16, v150
	v_add_f32_e32 v106, v116, v106
	v_add_f32_e32 v107, v107, v108
	v_add_f32_e32 v112, v106, v107
	v_mul_f32_e64 v106, |v112|, s82
	v_exp_f32_e32 v106, v106
	v_fmamk_f32 v107, v105, 0xbd800000, v104
	v_max_f32_e64 v105, -v115, 0
	v_add_f32_e32 v106, 1.0, v106
	v_log_f32_e32 v113, v106
	v_fmac_f32_e32 v105, 0x3f317218, v114
	v_fmamk_f32 v106, v105, 0xbd800000, v107
	v_max_f32_e64 v105, -v112, 0
	v_fmac_f32_e32 v105, 0x3f317218, v113
	s_waitcnt lgkmcnt(7)
	v_mul_f32_e32 v109, v3, v153
	v_fmac_f32_e32 v109, v2, v152
	v_mul_f32_e32 v108, v5, v155
	v_fmac_f32_e32 v108, v4, v154
	v_add_f32_e32 v108, v109, v108
	v_add_f32_e32 v116, v79, v108
	s_waitcnt lgkmcnt(6)
	v_mul_f32_e32 v113, v7, v157
	v_fmac_f32_e32 v113, v6, v156
	v_mul_f32_e32 v112, v9, v159
	v_fmac_f32_e32 v112, v8, v158
	v_add_f32_e32 v112, v113, v112
	v_add_f32_e32 v116, v116, v112
	s_waitcnt lgkmcnt(5)
	v_mul_f32_e32 v109, v11, v161
	v_fmac_f32_e32 v109, v10, v160
	v_mul_f32_e32 v108, v13, v163
	v_fmac_f32_e32 v108, v12, v162
	v_add_f32_e32 v108, v109, v108
	v_add_f32_e32 v116, v116, v108
	s_waitcnt lgkmcnt(4)
	v_mul_f32_e32 v108, v15, v165
	v_mul_f32_e32 v109, v17, v167
	v_fmac_f32_e32 v108, v14, v164
	v_fmac_f32_e32 v109, v16, v166
	v_add_f32_e32 v112, v108, v109
	v_add_f32_e32 v116, v116, v112
	v_mul_f32_e64 v112, |v116|, s82
	v_exp_f32_e32 v117, v112
	s_waitcnt lgkmcnt(3)
	v_mul_f32_e32 v109, v3, v169
	v_fmac_f32_e32 v109, v2, v168
	v_mul_f32_e32 v108, v5, v171
	v_fmac_f32_e32 v108, v4, v170
	v_add_f32_e32 v108, v109, v108
	s_waitcnt lgkmcnt(2)
	v_mul_f32_e32 v113, v7, v173
	v_add_f32_e32 v118, v79, v108
	v_fmac_f32_e32 v113, v6, v172
	v_mul_f32_e32 v112, v9, v175
	v_fmac_f32_e32 v112, v8, v174
	v_add_f32_e32 v112, v113, v112
	v_add_f32_e32 v118, v118, v112
	s_waitcnt lgkmcnt(1)
	v_mul_f32_e32 v109, v11, v177
	v_fmac_f32_e32 v109, v10, v176
	v_mul_f32_e32 v108, v13, v179
	v_fmac_f32_e32 v108, v12, v178
	v_add_f32_e32 v108, v109, v108
	s_waitcnt lgkmcnt(0)
	v_mul_f32_e32 v109, v15, v181
	v_mul_f32_e32 v110, v17, v183
	v_fmac_f32_e32 v109, v14, v180
	v_fmac_f32_e32 v110, v16, v182
	v_add_f32_e32 v108, v118, v108
	v_add_f32_e32 v109, v109, v110
	v_add_f32_e32 v108, v108, v109
	v_mul_f32_e64 v109, |v108|, s82
	v_exp_f32_e32 v109, v109
	v_add_f32_e32 v110, 1.0, v117
	v_log_f32_e32 v110, v110
	v_max_f32_e64 v111, -v116, 0
	v_add_f32_e32 v109, 1.0, v109
	v_log_f32_e32 v112, v109
	v_fmamk_f32 v105, v105, 0xbd800000, v106
	v_fmac_f32_e32 v111, 0x3f317218, v110
	v_max_f32_e64 v108, -v108, 0
	v_fmamk_f32 v109, v111, 0xbd800000, v105
	v_fmac_f32_e32 v108, 0x3f317218, v112
	v_fmamk_f32 v108, v108, 0xbd800000, v109
	ds_write_b32 v78, v108
	s_waitcnt vmcnt(7)
	ds_write_b128 v54, v[18:21]
	s_waitcnt vmcnt(6)
	ds_write_b128 v54, v[22:25] offset:33792
	s_waitcnt vmcnt(5)
	ds_write_b128 v56, v[26:29]
	s_waitcnt vmcnt(4)
	ds_write_b128 v56, v[30:33] offset:33792
	s_waitcnt vmcnt(3)
	ds_write_b128 v58, v[34:37]
	s_waitcnt vmcnt(2)
	ds_write_b128 v58, v[38:41] offset:33792
	s_waitcnt vmcnt(1)
	ds_write_b128 v60, v[42:45]
	s_waitcnt vmcnt(0)
	ds_write_b128 v60, v[46:49] offset:33792
	s_waitcnt lgkmcnt(0)
	s_barrier
	ds_read_b32 v18, v57
	ds_read_u16 v20, v59 offset:33792
	ds_read_u16 v21, v59 offset:34320
	ds_read_u16 v22, v59 offset:34848
	ds_read_u16 v23, v59 offset:35376
	ds_read_u16 v24, v59 offset:35904
	ds_read_u16 v25, v59 offset:36432
	ds_read_u16 v26, v59 offset:36960
	s_waitcnt lgkmcnt(7)
	v_cndmask_b32_e64 v19, v18, 0, s[4:5]
	v_add_f32_e32 v27, v86, v19
	v_mul_f32_e32 v36, 0x3fb8aa3b, v27
	v_mul_f32_e32 v27, 0xbfb8aa3b, v27
	v_exp_f32_e32 v27, v27
	s_waitcnt lgkmcnt(6)
	v_lshlrev_b32_e32 v20, 16, v20
	v_add_f32_e32 v0, v0, v19
	s_waitcnt lgkmcnt(5)
	v_lshlrev_b32_e32 v21, 16, v21
	v_mul_f32_e32 v20, v27, v20
	v_mul_f32_e32 v27, 0x3fb8aa3b, v0
	v_mul_f32_e32 v0, 0xbfb8aa3b, v0
	v_exp_f32_e32 v0, v0
	ds_read_u16 v28, v59
	ds_read_u16 v29, v59 offset:528
	ds_read_u16 v30, v59 offset:1056
	ds_read_u16 v31, v59 offset:1584
	ds_read_u16 v32, v59 offset:2112
	ds_read_u16 v33, v59 offset:2640
	ds_read_u16 v34, v59 offset:3168
	ds_read_u16 v35, v59 offset:50160
	v_exp_f32_e32 v27, v27
	v_cvt_pk_bf16_f32 v20, v20, s0
	v_mul_f32_e32 v0, v0, v21
	v_cvt_pk_bf16_f32 v0, v0, s0
	ds_write_b16 v59, v0 offset:34320
	v_add_f32_e32 v0, v69, v19
	s_waitcnt lgkmcnt(13)
	v_lshlrev_b32_e32 v21, 16, v22
	v_mul_f32_e32 v22, 0x3fb8aa3b, v0
	v_mul_f32_e32 v0, 0xbfb8aa3b, v0
	v_exp_f32_e32 v0, v0
	ds_write_b16 v59, v20 offset:33792
	s_waitcnt lgkmcnt(8)
	v_lshlrev_b32_e32 v20, 16, v29
	v_mul_f32_e32 v20, 0x3d800000, v20
	v_mul_f32_e32 v20, v27, v20
	v_exp_f32_e32 v22, v22
	v_cvt_pk_bf16_f32 v20, v20, s0
	v_mul_f32_e32 v0, v0, v21
	ds_write_b16 v59, v20 offset:528
	s_waitcnt lgkmcnt(8)
	v_lshlrev_b32_e32 v20, 16, v30
	v_cvt_pk_bf16_f32 v0, v0, s0
	v_mul_f32_e32 v20, 0x3d800000, v20
	ds_write_b16 v59, v0 offset:34848
	v_add_f32_e32 v0, v81, v19
	v_mul_f32_e32 v20, v22, v20
	v_mul_f32_e32 v22, 0x3fb8aa3b, v0
	v_mul_f32_e32 v0, 0xbfb8aa3b, v0
	v_exp_f32_e32 v0, v0
	v_lshlrev_b32_e32 v21, 16, v23
	v_exp_f32_e32 v22, v22
	v_cvt_pk_bf16_f32 v20, v20, s0
	v_mul_f32_e32 v0, v0, v21
	ds_write_b16 v59, v20 offset:1056
	s_waitcnt lgkmcnt(9)
	v_lshlrev_b32_e32 v20, 16, v31
	v_cvt_pk_bf16_f32 v0, v0, s0
	v_mul_f32_e32 v20, 0x3d800000, v20
	ds_write_b16 v59, v0 offset:35376
	v_add_f32_e32 v0, v80, v19
	v_mul_f32_e32 v20, v22, v20
	v_mul_f32_e32 v22, 0x3fb8aa3b, v0
	v_mul_f32_e32 v0, 0xbfb8aa3b, v0
	v_exp_f32_e32 v0, v0
	v_lshlrev_b32_e32 v21, 16, v24
	v_exp_f32_e32 v22, v22
	v_cvt_pk_bf16_f32 v20, v20, s0
	v_mul_f32_e32 v0, v0, v21
	ds_write_b16 v59, v20 offset:1584
	s_waitcnt lgkmcnt(10)
	v_lshlrev_b32_e32 v20, 16, v32
	v_cvt_pk_bf16_f32 v0, v0, s0
	v_mul_f32_e32 v20, 0x3d800000, v20
	ds_write_b16 v59, v0 offset:35904
	v_add_f32_e32 v0, v82, v19
	v_mul_f32_e32 v20, v22, v20
	v_mul_f32_e32 v22, 0x3fb8aa3b, v0
	v_mul_f32_e32 v0, 0xbfb8aa3b, v0
	v_exp_f32_e32 v0, v0
	v_lshlrev_b32_e32 v21, 16, v25
	v_exp_f32_e32 v22, v22
	v_cvt_pk_bf16_f32 v20, v20, s0
	v_mul_f32_e32 v0, v0, v21
	ds_write_b16 v59, v20 offset:2112
	s_waitcnt lgkmcnt(11)
	v_lshlrev_b32_e32 v20, 16, v33
	v_cvt_pk_bf16_f32 v0, v0, s0
	v_mul_f32_e32 v20, 0x3d800000, v20
	ds_write_b16 v59, v0 offset:36432
	v_add_f32_e32 v0, v83, v19
	v_mul_f32_e32 v20, v22, v20
	v_mul_f32_e32 v22, 0x3fb8aa3b, v0
	v_mul_f32_e32 v0, 0xbfb8aa3b, v0
	v_exp_f32_e32 v0, v0
	v_exp_f32_e32 v36, v36
	v_lshlrev_b32_e32 v21, 16, v26
	v_exp_f32_e32 v22, v22
	v_cvt_pk_bf16_f32 v20, v20, s0
	v_mul_f32_e32 v0, v0, v21
	v_lshlrev_b32_e32 v28, 16, v28
	ds_write_b16 v59, v20 offset:2640
	s_waitcnt lgkmcnt(12)
	v_lshlrev_b32_e32 v20, 16, v34
	v_cvt_pk_bf16_f32 v0, v0, s0
	v_mul_f32_e32 v28, 0x3d800000, v28
	v_mul_f32_e32 v20, 0x3d800000, v20
	ds_write_b16 v59, v0 offset:36960
	v_add_f32_e32 v0, v85, v19
	v_mul_f32_e32 v28, v36, v28
	v_mul_f32_e32 v20, v22, v20
	v_mul_f32_e32 v37, 0x3fb8aa3b, v0
	v_mul_f32_e32 v0, 0xbfb8aa3b, v0
	v_cvt_pk_bf16_f32 v28, v28, s0
	v_cvt_pk_bf16_f32 v20, v20, s0
	v_exp_f32_e32 v0, v0
	ds_write_b16 v59, v28
	ds_write_b16 v59, v20 offset:3168
	ds_read_u16 v20, v59 offset:3696
	ds_read_u16 v21, v59 offset:4224
	ds_read_u16 v22, v59 offset:4752
	ds_read_u16 v23, v59 offset:5280
	ds_read_u16 v24, v59 offset:5808
	ds_read_u16 v25, v59 offset:6336
	ds_read_u16 v26, v59 offset:6864
	ds_read_u16 v27, v59 offset:7392
	ds_read_u16 v28, v59 offset:37488
	ds_read_u16 v29, v59 offset:38016
	ds_read_u16 v30, v59 offset:38544
	ds_read_u16 v31, v59 offset:39072
	ds_read_u16 v32, v59 offset:39600
	ds_read_u16 v33, v59 offset:40128
	ds_read_u16 v34, v59 offset:40656
	ds_read_u16 v36, v59 offset:41184
	s_waitcnt lgkmcnt(7)
	v_lshlrev_b32_e32 v28, 16, v28
	v_mul_f32_e32 v0, v0, v28
	v_exp_f32_e32 v37, v37
	v_cvt_pk_bf16_f32 v0, v0, s0
	ds_write_b16 v59, v0 offset:37488
	v_add_f32_e32 v0, v84, v19
	v_lshlrev_b32_e32 v20, 16, v20
	v_mul_f32_e32 v28, 0x3fb8aa3b, v0
	v_mul_f32_e32 v0, 0xbfb8aa3b, v0
	v_mul_f32_e32 v20, 0x3d800000, v20
	v_exp_f32_e32 v0, v0
	v_mul_f32_e32 v20, v37, v20
	v_exp_f32_e32 v28, v28
	v_cvt_pk_bf16_f32 v20, v20, s0
	ds_write_b16 v59, v20 offset:3696
	v_lshlrev_b32_e32 v20, 16, v21
	s_waitcnt lgkmcnt(8)
	v_lshlrev_b32_e32 v21, 16, v29
	v_mul_f32_e32 v20, 0x3d800000, v20
	v_mul_f32_e32 v0, v0, v21
	v_mul_f32_e32 v20, v28, v20
	v_cvt_pk_bf16_f32 v0, v0, s0
	v_cvt_pk_bf16_f32 v20, v20, s0
	ds_write_b16 v59, v0 offset:38016
	v_add_f32_e32 v0, v87, v19
	ds_write_b16 v59, v20 offset:4224
	v_lshlrev_b32_e32 v20, 16, v22
	v_mul_f32_e32 v22, 0x3fb8aa3b, v0
	v_mul_f32_e32 v0, 0xbfb8aa3b, v0
	v_exp_f32_e32 v0, v0
	s_waitcnt lgkmcnt(9)
	v_lshlrev_b32_e32 v21, 16, v30
	v_exp_f32_e32 v22, v22
	v_mul_f32_e32 v20, 0x3d800000, v20
	v_mul_f32_e32 v0, v0, v21
	v_cvt_pk_bf16_f32 v0, v0, s0
	ds_write_b16 v59, v0 offset:38544
	v_add_f32_e32 v0, v88, v19
	v_mul_f32_e32 v20, v22, v20
	v_mul_f32_e32 v22, 0x3fb8aa3b, v0
	v_mul_f32_e32 v0, 0xbfb8aa3b, v0
	v_exp_f32_e32 v0, v0
	s_waitcnt lgkmcnt(9)
	v_lshlrev_b32_e32 v21, 16, v31
	v_exp_f32_e32 v22, v22
	v_cvt_pk_bf16_f32 v20, v20, s0
	v_mul_f32_e32 v0, v0, v21
	ds_write_b16 v59, v20 offset:4752
	v_lshlrev_b32_e32 v20, 16, v23
	v_cvt_pk_bf16_f32 v0, v0, s0
	v_mul_f32_e32 v20, 0x3d800000, v20
	ds_write_b16 v59, v0 offset:39072
	v_add_f32_e32 v0, v90, v19
	v_mul_f32_e32 v20, v22, v20
	v_mul_f32_e32 v22, 0x3fb8aa3b, v0
	v_mul_f32_e32 v0, 0xbfb8aa3b, v0
	v_exp_f32_e32 v0, v0
	s_waitcnt lgkmcnt(10)
	v_lshlrev_b32_e32 v21, 16, v32
	v_exp_f32_e32 v22, v22
	v_cvt_pk_bf16_f32 v20, v20, s0
	v_mul_f32_e32 v0, v0, v21
	ds_write_b16 v59, v20 offset:5280
	v_lshlrev_b32_e32 v20, 16, v24
	v_cvt_pk_bf16_f32 v0, v0, s0
	v_mul_f32_e32 v20, 0x3d800000, v20
	ds_write_b16 v59, v0 offset:39600
	v_add_f32_e32 v0, v89, v19
	v_mul_f32_e32 v20, v22, v20
	v_mul_f32_e32 v22, 0x3fb8aa3b, v0
	v_mul_f32_e32 v0, 0xbfb8aa3b, v0
	v_exp_f32_e32 v0, v0
	s_waitcnt lgkmcnt(11)
	v_lshlrev_b32_e32 v21, 16, v33
	v_exp_f32_e32 v22, v22
	v_cvt_pk_bf16_f32 v20, v20, s0
	v_mul_f32_e32 v0, v0, v21
	ds_write_b16 v59, v20 offset:5808
	v_lshlrev_b32_e32 v20, 16, v25
	v_cvt_pk_bf16_f32 v0, v0, s0
	v_mul_f32_e32 v20, 0x3d800000, v20
	ds_write_b16 v59, v0 offset:40128
	v_add_f32_e32 v0, v91, v19
	v_mul_f32_e32 v20, v22, v20
	v_mul_f32_e32 v22, 0x3fb8aa3b, v0
	v_mul_f32_e32 v0, 0xbfb8aa3b, v0
	v_exp_f32_e32 v0, v0
	s_waitcnt lgkmcnt(12)
	v_lshlrev_b32_e32 v21, 16, v34
	v_exp_f32_e32 v22, v22
	v_cvt_pk_bf16_f32 v20, v20, s0
	v_mul_f32_e32 v0, v0, v21
	ds_write_b16 v59, v20 offset:6336
	v_lshlrev_b32_e32 v20, 16, v26
	v_cvt_pk_bf16_f32 v0, v0, s0
	v_mul_f32_e32 v20, 0x3d800000, v20
	ds_write_b16 v59, v0 offset:40656
	v_add_f32_e32 v0, v92, v19
	v_mul_f32_e32 v20, v22, v20
	v_mul_f32_e32 v22, 0x3fb8aa3b, v0
	v_mul_f32_e32 v0, 0xbfb8aa3b, v0
	v_exp_f32_e32 v0, v0
	s_waitcnt lgkmcnt(13)
	v_lshlrev_b32_e32 v21, 16, v36
	v_exp_f32_e32 v22, v22
	v_cvt_pk_bf16_f32 v20, v20, s0
	v_mul_f32_e32 v0, v0, v21
	ds_write_b16 v59, v20 offset:6864
	v_lshlrev_b32_e32 v20, 16, v27
	v_cvt_pk_bf16_f32 v0, v0, s0
	v_mul_f32_e32 v20, 0x3d800000, v20
	ds_write_b16 v59, v0 offset:41184
	v_add_f32_e32 v0, v94, v19
	v_mul_f32_e32 v20, v22, v20
	v_mul_f32_e32 v37, 0x3fb8aa3b, v0
	v_mul_f32_e32 v0, 0xbfb8aa3b, v0
	v_cvt_pk_bf16_f32 v20, v20, s0
	v_exp_f32_e32 v0, v0
	ds_write_b16 v59, v20 offset:7392
	ds_read_u16 v20, v59 offset:7920
	ds_read_u16 v21, v59 offset:8448
	ds_read_u16 v22, v59 offset:8976
	ds_read_u16 v23, v59 offset:9504
	ds_read_u16 v24, v59 offset:10032
	ds_read_u16 v25, v59 offset:10560
	ds_read_u16 v26, v59 offset:11088
	ds_read_u16 v27, v59 offset:11616
	ds_read_u16 v28, v59 offset:41712
	ds_read_u16 v29, v59 offset:42240
	ds_read_u16 v30, v59 offset:42768
	ds_read_u16 v31, v59 offset:43296
	ds_read_u16 v32, v59 offset:43824
	ds_read_u16 v33, v59 offset:44352
	ds_read_u16 v34, v59 offset:44880
	ds_read_u16 v36, v59 offset:45408
	s_waitcnt lgkmcnt(7)
	v_lshlrev_b32_e32 v28, 16, v28
	v_mul_f32_e32 v0, v0, v28
	v_exp_f32_e32 v37, v37
	v_cvt_pk_bf16_f32 v0, v0, s0
	ds_write_b16 v59, v0 offset:41712
	v_add_f32_e32 v0, v93, v19
	v_lshlrev_b32_e32 v20, 16, v20
	v_mul_f32_e32 v28, 0x3fb8aa3b, v0
	v_mul_f32_e32 v0, 0xbfb8aa3b, v0
	v_mul_f32_e32 v20, 0x3d800000, v20
	v_exp_f32_e32 v0, v0
	v_mul_f32_e32 v20, v37, v20
	v_exp_f32_e32 v28, v28
	v_cvt_pk_bf16_f32 v20, v20, s0
	ds_write_b16 v59, v20 offset:7920
	v_lshlrev_b32_e32 v20, 16, v21
	s_waitcnt lgkmcnt(8)
	v_lshlrev_b32_e32 v21, 16, v29
	v_mul_f32_e32 v20, 0x3d800000, v20
	v_mul_f32_e32 v0, v0, v21
	v_mul_f32_e32 v20, v28, v20
	v_cvt_pk_bf16_f32 v0, v0, s0
	v_cvt_pk_bf16_f32 v20, v20, s0
	ds_write_b16 v59, v0 offset:42240
	v_add_f32_e32 v0, v95, v19
	ds_write_b16 v59, v20 offset:8448
	v_lshlrev_b32_e32 v20, 16, v22
	v_mul_f32_e32 v22, 0x3fb8aa3b, v0
	v_mul_f32_e32 v0, 0xbfb8aa3b, v0
	v_exp_f32_e32 v0, v0
	s_waitcnt lgkmcnt(9)
	v_lshlrev_b32_e32 v21, 16, v30
	v_exp_f32_e32 v22, v22
	v_mul_f32_e32 v20, 0x3d800000, v20
	v_mul_f32_e32 v0, v0, v21
	v_cvt_pk_bf16_f32 v0, v0, s0
	ds_write_b16 v59, v0 offset:42768
	v_add_f32_e32 v0, v96, v19
	v_mul_f32_e32 v20, v22, v20
	v_mul_f32_e32 v22, 0x3fb8aa3b, v0
	v_mul_f32_e32 v0, 0xbfb8aa3b, v0
	v_exp_f32_e32 v0, v0
	s_waitcnt lgkmcnt(9)
	v_lshlrev_b32_e32 v21, 16, v31
	v_exp_f32_e32 v22, v22
	v_cvt_pk_bf16_f32 v20, v20, s0
	v_mul_f32_e32 v0, v0, v21
	ds_write_b16 v59, v20 offset:8976
	v_lshlrev_b32_e32 v20, 16, v23
	v_cvt_pk_bf16_f32 v0, v0, s0
	v_mul_f32_e32 v20, 0x3d800000, v20
	ds_write_b16 v59, v0 offset:43296
	v_add_f32_e32 v0, v98, v19
	v_mul_f32_e32 v20, v22, v20
	v_mul_f32_e32 v22, 0x3fb8aa3b, v0
	v_mul_f32_e32 v0, 0xbfb8aa3b, v0
	v_exp_f32_e32 v0, v0
	s_waitcnt lgkmcnt(10)
	v_lshlrev_b32_e32 v21, 16, v32
	v_exp_f32_e32 v22, v22
	v_cvt_pk_bf16_f32 v20, v20, s0
	v_mul_f32_e32 v0, v0, v21
	ds_write_b16 v59, v20 offset:9504
	v_lshlrev_b32_e32 v20, 16, v24
	v_cvt_pk_bf16_f32 v0, v0, s0
	v_mul_f32_e32 v20, 0x3d800000, v20
	ds_write_b16 v59, v0 offset:43824
	v_add_f32_e32 v0, v97, v19
	v_mul_f32_e32 v20, v22, v20
	v_mul_f32_e32 v22, 0x3fb8aa3b, v0
	v_mul_f32_e32 v0, 0xbfb8aa3b, v0
	v_exp_f32_e32 v0, v0
	s_waitcnt lgkmcnt(11)
	v_lshlrev_b32_e32 v21, 16, v33
	v_exp_f32_e32 v22, v22
	v_cvt_pk_bf16_f32 v20, v20, s0
	v_mul_f32_e32 v0, v0, v21
	ds_write_b16 v59, v20 offset:10032
	v_lshlrev_b32_e32 v20, 16, v25
	v_cvt_pk_bf16_f32 v0, v0, s0
	v_mul_f32_e32 v20, 0x3d800000, v20
	ds_write_b16 v59, v0 offset:44352
	v_add_f32_e32 v0, v99, v19
	v_mul_f32_e32 v20, v22, v20
	v_mul_f32_e32 v22, 0x3fb8aa3b, v0
	v_mul_f32_e32 v0, 0xbfb8aa3b, v0
	v_exp_f32_e32 v0, v0
	s_waitcnt lgkmcnt(12)
	v_lshlrev_b32_e32 v21, 16, v34
	v_exp_f32_e32 v22, v22
	v_cvt_pk_bf16_f32 v20, v20, s0
	v_mul_f32_e32 v0, v0, v21
	ds_write_b16 v59, v20 offset:10560
	v_lshlrev_b32_e32 v20, 16, v26
	v_cvt_pk_bf16_f32 v0, v0, s0
	v_mul_f32_e32 v20, 0x3d800000, v20
	ds_write_b16 v59, v0 offset:44880
	v_add_f32_e32 v0, v100, v19
	v_mul_f32_e32 v20, v22, v20
	v_mul_f32_e32 v22, 0x3fb8aa3b, v0
	v_mul_f32_e32 v0, 0xbfb8aa3b, v0
	v_exp_f32_e32 v0, v0
	s_waitcnt lgkmcnt(13)
	v_lshlrev_b32_e32 v21, 16, v36
	v_exp_f32_e32 v22, v22
	v_cvt_pk_bf16_f32 v20, v20, s0
	v_mul_f32_e32 v0, v0, v21
	ds_write_b16 v59, v20 offset:11088
	v_lshlrev_b32_e32 v20, 16, v27
	v_cvt_pk_bf16_f32 v0, v0, s0
	v_mul_f32_e32 v20, 0x3d800000, v20
	ds_write_b16 v59, v0 offset:45408
	v_add_f32_e32 v0, v102, v19
	v_mul_f32_e32 v20, v22, v20
	v_mul_f32_e32 v37, 0x3fb8aa3b, v0
	v_mul_f32_e32 v0, 0xbfb8aa3b, v0
	v_cvt_pk_bf16_f32 v20, v20, s0
	v_exp_f32_e32 v0, v0
	ds_write_b16 v59, v20 offset:11616
	ds_read_u16 v20, v59 offset:12144
	ds_read_u16 v21, v59 offset:12672
	ds_read_u16 v22, v59 offset:13200
	ds_read_u16 v23, v59 offset:13728
	ds_read_u16 v24, v59 offset:14256
	ds_read_u16 v25, v59 offset:14784
	ds_read_u16 v26, v59 offset:15312
	ds_read_u16 v27, v59 offset:15840
	ds_read_u16 v28, v59 offset:45936
	ds_read_u16 v29, v59 offset:46464
	ds_read_u16 v30, v59 offset:46992
	ds_read_u16 v31, v59 offset:47520
	ds_read_u16 v32, v59 offset:48048
	ds_read_u16 v33, v59 offset:48576
	ds_read_u16 v34, v59 offset:49104
	ds_read_u16 v36, v59 offset:49632
	s_waitcnt lgkmcnt(7)
	v_lshlrev_b32_e32 v28, 16, v28
	v_mul_f32_e32 v0, v0, v28
	v_exp_f32_e32 v37, v37
	v_cvt_pk_bf16_f32 v0, v0, s0
	ds_write_b16 v59, v0 offset:45936
	v_add_f32_e32 v0, v101, v19
	v_lshlrev_b32_e32 v20, 16, v20
	v_mul_f32_e32 v28, 0x3fb8aa3b, v0
	v_mul_f32_e32 v0, 0xbfb8aa3b, v0
	v_mul_f32_e32 v20, 0x3d800000, v20
	v_exp_f32_e32 v0, v0
	v_mul_f32_e32 v20, v37, v20
	v_exp_f32_e32 v28, v28
	v_cvt_pk_bf16_f32 v20, v20, s0
	ds_write_b16 v59, v20 offset:12144
	v_lshlrev_b32_e32 v20, 16, v21
	s_waitcnt lgkmcnt(8)
	v_lshlrev_b32_e32 v21, 16, v29
	v_mul_f32_e32 v20, 0x3d800000, v20
	v_mul_f32_e32 v0, v0, v21
	v_mul_f32_e32 v20, v28, v20
	v_cvt_pk_bf16_f32 v0, v0, s0
	v_cvt_pk_bf16_f32 v20, v20, s0
	ds_write_b16 v59, v0 offset:46464
	v_add_f32_e32 v0, v103, v19
	ds_write_b16 v59, v20 offset:12672
	v_lshlrev_b32_e32 v20, 16, v22
	v_mul_f32_e32 v22, 0x3fb8aa3b, v0
	v_mul_f32_e32 v0, 0xbfb8aa3b, v0
	v_exp_f32_e32 v0, v0
	s_waitcnt lgkmcnt(9)
	v_lshlrev_b32_e32 v21, 16, v30
	v_exp_f32_e32 v22, v22
	v_mul_f32_e32 v20, 0x3d800000, v20
	v_mul_f32_e32 v0, v0, v21
	v_cvt_pk_bf16_f32 v0, v0, s0
	ds_write_b16 v59, v0 offset:46992
	v_add_f32_e32 v0, v104, v19
	v_mul_f32_e32 v20, v22, v20
	v_mul_f32_e32 v22, 0x3fb8aa3b, v0
	v_mul_f32_e32 v0, 0xbfb8aa3b, v0
	v_exp_f32_e32 v0, v0
	s_waitcnt lgkmcnt(9)
	v_lshlrev_b32_e32 v21, 16, v31
	v_exp_f32_e32 v22, v22
	v_cvt_pk_bf16_f32 v20, v20, s0
	v_mul_f32_e32 v0, v0, v21
	ds_write_b16 v59, v20 offset:13200
	v_lshlrev_b32_e32 v20, 16, v23
	v_cvt_pk_bf16_f32 v0, v0, s0
	v_mul_f32_e32 v20, 0x3d800000, v20
	ds_write_b16 v59, v0 offset:47520
	v_add_f32_e32 v0, v107, v19
	v_mul_f32_e32 v20, v22, v20
	v_mul_f32_e32 v22, 0x3fb8aa3b, v0
	v_mul_f32_e32 v0, 0xbfb8aa3b, v0
	v_exp_f32_e32 v0, v0
	s_waitcnt lgkmcnt(10)
	v_lshlrev_b32_e32 v21, 16, v32
	v_exp_f32_e32 v22, v22
	v_cvt_pk_bf16_f32 v20, v20, s0
	v_mul_f32_e32 v0, v0, v21
	ds_write_b16 v59, v20 offset:13728
	v_lshlrev_b32_e32 v20, 16, v24
	v_cvt_pk_bf16_f32 v0, v0, s0
	v_mul_f32_e32 v20, 0x3d800000, v20
	ds_write_b16 v59, v0 offset:48048
	v_add_f32_e32 v0, v106, v19
	v_mul_f32_e32 v20, v22, v20
	v_mul_f32_e32 v22, 0x3fb8aa3b, v0
	v_mul_f32_e32 v0, 0xbfb8aa3b, v0
	v_exp_f32_e32 v0, v0
	s_waitcnt lgkmcnt(11)
	v_lshlrev_b32_e32 v21, 16, v33
	v_exp_f32_e32 v22, v22
	v_cvt_pk_bf16_f32 v20, v20, s0
	v_mul_f32_e32 v0, v0, v21
	ds_write_b16 v59, v20 offset:14256
	v_lshlrev_b32_e32 v20, 16, v25
	v_cvt_pk_bf16_f32 v0, v0, s0
	v_mul_f32_e32 v20, 0x3d800000, v20
	ds_write_b16 v59, v0 offset:48576
	v_add_f32_e32 v0, v105, v19
	v_mul_f32_e32 v20, v22, v20
	v_mul_f32_e32 v22, 0x3fb8aa3b, v0
	v_mul_f32_e32 v0, 0xbfb8aa3b, v0
	v_exp_f32_e32 v0, v0
	s_waitcnt lgkmcnt(12)
	v_lshlrev_b32_e32 v21, 16, v34
	v_exp_f32_e32 v22, v22
	v_cvt_pk_bf16_f32 v20, v20, s0
	v_mul_f32_e32 v0, v0, v21
	ds_write_b16 v59, v20 offset:14784
	v_lshlrev_b32_e32 v20, 16, v26
	v_cvt_pk_bf16_f32 v0, v0, s0
	v_mul_f32_e32 v20, 0x3d800000, v20
	ds_write_b16 v59, v0 offset:49104
	v_add_f32_e32 v0, v109, v19
	v_mul_f32_e32 v20, v22, v20
	v_mul_f32_e32 v22, 0x3fb8aa3b, v0
	v_exp_f32_e32 v22, v22
	v_mul_f32_e32 v0, 0xbfb8aa3b, v0
	v_cvt_pk_bf16_f32 v20, v20, s0
	v_exp_f32_e32 v0, v0
	ds_write_b16 v59, v20 offset:15312
	v_lshlrev_b32_e32 v20, 16, v27
	v_mul_f32_e32 v20, 0x3d800000, v20
	s_waitcnt lgkmcnt(14)
	v_lshlrev_b32_e32 v21, 16, v36
	v_mul_f32_e32 v20, v22, v20
	v_cvt_pk_bf16_f32 v20, v20, s0
	v_mul_f32_e32 v0, v0, v21
	ds_write_b16 v59, v20 offset:15840
	ds_read_u16 v20, v59 offset:16368
	v_cvt_pk_bf16_f32 v0, v0, s0
	ds_write_b16 v59, v0 offset:49632
	v_add_f32_e32 v0, v19, v108
	v_mul_f32_e32 v21, 0x3fb8aa3b, v0
	v_mul_f32_e32 v0, 0xbfb8aa3b, v0
	v_exp_f32_e32 v21, v21
	v_exp_f32_e32 v0, v0
	s_waitcnt lgkmcnt(1)
	v_lshlrev_b32_e32 v19, 16, v20
	v_lshlrev_b32_e32 v20, 16, v35
	v_mul_f32_e32 v19, 0x3d800000, v19
	v_mul_f32_e32 v19, v21, v19
	v_mul_f32_e32 v0, v0, v20
	v_cvt_pk_bf16_f32 v19, v19, s0
	v_cvt_pk_bf16_f32 v0, v0, s0
	ds_write_b16 v59, v19 offset:16368
	ds_write_b16 v59, v0 offset:50160
	s_and_saveexec_b64 s[64:65], s[4:5]
	s_cbranch_execz .LBB0_613
	ds_read_b32 v0, v57 offset:1024
	s_ashr_i32 s37, s36, 31
	s_lshl_b64 s[66:67], s[36:37], 10
	s_waitcnt lgkmcnt(0)
	v_add_f32_e32 v0, v18, v0
	v_mul_f32_e32 v0, 0x3fb8aa3b, v0
	v_exp_f32_e32 v0, v0
	v_lshl_add_u64 v[18:19], v[62:63], 0, s[66:67]
	ds_write_b32 v51, v0
	global_store_dword v[18:19], v0, off
